# attention main loop hand-scheduled: reference folded into QK via an extra MFMA k-slice, sampled lazy reference refresh (T=8), packed row sums; on top of GEMM prefetch changes
# speedup vs baseline: 1.0383x; 1.0111x over previous
; DI int opq(int x) { asm volatile("" : "+v"(x)); return x; }
; DI void attn_tile8(const Params& p, int bh, int qt, char* smem) {
;   const int b = bh >> 3, hh = bh & 7;
;   const int nkt = (qt < 1) ? 2 : 34;
;   const int tid = opq(threadIdx.x), lane = tid & 63, w = tid >> 6, lr = lane & 31, lh = lane >> 5;
;   const size_t rowbase = (size_t)b * TPB;
;   const size_t qrow = rowbase + qt * 256 + w * 32 + lr;
;   constexpr int STAGE = 43520, VOFF = 26624, VROW = 264;
;   bf16x8 qf[6];
;   {
;     const u16* qp = p.Q + qrow * 768 + hh * 96 + lh * 8;
; #pragma unroll
;     for (int s = 0; s < 6; ++s) qf[s] = *(const bf16x8*)(qp + 16 * s);
;   }
;   u32x4 rk[3], rv[2];
;   auto load_tiles = [&](int kt) {
; #pragma unroll
;     for (int i = 0; i < 3; ++i) {
;       const int idx = tid + 512 * i, key = idx / 12, ch = idx % 12;
;       const size_t kr = rowbase + kt * 128 + key;
;       rk[i] = (ch < 8) ? *(const u32x4*)(p.Kn + kr * 512 + hh * 64 + ch * 8) : *(const u32x4*)(p.KR + kr * 32 + (ch - 8) * 8);
;     }
; #pragma unroll
;     for (int i = 0; i < 2; ++i) {
;       const int idx = tid + 512 * i, vd = idx >> 4, ch = idx & 15;
;       rv[i] = *(const u32x4*)(p.Vt + ((size_t)bh * 64 + vd) * TPB + kt * 128 + ch * 8);
;     }
;   };
.LBB1_1167:
	s_andn2_saveexec_b64 s[16:17], s[16:17]
	s_cbranch_execz .LBB1_1140
	v_lshlrev_b32_e32 v2, 8, v33
	v_mov_b32_e32 v6, v192
	v_and_b32_e32 v2, 0xf00, v2
	v_ashrrev_i32_e32 v26, 7, v33
	v_add_u32_e32 v194, 0x100, v2
	s_movk_i32 s4, 0x1100
	v_ashrrev_i32_e32 v4, 1, v6
	v_and_b32_e32 v27, 31, v6
	v_mad_i64_i32 v[2:3], s[2:3], v26, s4, v[194:195]
	v_and_b32_e32 v4, 0xffffffe0, v4
	v_ashrrev_i32_e32 v0, 4, v33
	v_ashrrev_i32_e32 v5, 31, v4
	v_or_b32_e32 v2, v2, v27
	v_and_b32_e32 v1, 7, v0
	v_lshl_add_u64 v[140:141], v[2:3], 0, v[4:5]
	v_mov_b64_e32 v[2:3], s[66:67]
	s_movk_i32 s5, 0x600
	v_mad_u64_u32 v[2:3], s[2:3], v140, s5, v[2:3]
	v_mul_u32_u24_e32 v4, 0x60, v1
	v_bfe_u32 v170, v6, 5, 1
	v_mad_i32_i24 v3, v141, s5, v3
	v_lshlrev_b32_e32 v194, 1, v4
	v_lshl_add_u64 v[2:3], v[2:3], 0, v[194:195]
	v_lshlrev_b32_e32 v194, 4, v170
	v_lshl_add_u64 v[2:3], v[2:3], 0, v[194:195]
	global_load_dwordx4 v[96:99], v[2:3], off
	global_load_dwordx4 v[100:103], v[2:3], off offset:32
	global_load_dwordx4 v[104:107], v[2:3], off offset:64
	global_load_dwordx4 v[108:111], v[2:3], off offset:96
	global_load_dwordx4 v[112:115], v[2:3], off offset:128
	global_load_dwordx4 v[116:119], v[2:3], off offset:160
	s_mov_b32 s2, 0x2aaaaaab
	v_mul_hi_i32 v2, v6, s2
	v_lshrrev_b32_e32 v3, 31, v2
	v_ashrrev_i32_e32 v2, 1, v2
	v_add_u32_e32 v2, v2, v3
	v_mul_lo_u32 v3, v2, 12
	v_sub_u32_e32 v4, v6, v3
	v_ashrrev_i32_e32 v3, 31, v2
	v_mad_i64_i32 v[10:11], s[2:3], v26, s4, v[2:3]
	s_movk_i32 s18, 0x1100
	v_cmp_gt_i32_e64 s[2:3], 8, v4
	v_cmp_lt_i32_e32 vcc, 7, v4
	v_lshlrev_b32_e32 v144, 4, v4
	s_and_saveexec_b64 s[4:5], vcc
	s_xor_b64 s[4:5], exec, s[4:5]
	v_lshlrev_b64 v[8:9], 6, v[10:11]
	v_lshl_add_u64 v[8:9], s[72:73], 0, v[8:9]
	v_mov_b32_e32 v145, v195
	s_movk_i32 s6, 0xff80
	v_lshl_add_u64 v[8:9], v[8:9], 0, v[144:145]
	s_mov_b32 s7, -1
	v_lshl_add_u64 v[8:9], v[8:9], 0, s[6:7]
	s_or_saveexec_b64 s[4:5], s[4:5]
	v_lshlrev_b32_e32 v4, 3, v4
	v_lshlrev_b32_e32 v18, 7, v1
	v_ashrrev_i32_e32 v7, 31, v4
	s_xor_b64 exec, exec, s[4:5]
	v_lshlrev_b64 v[8:9], 10, v[10:11]
	v_lshl_add_u64 v[8:9], s[68:69], 0, v[8:9]
	v_mov_b32_e32 v19, v195
	v_lshl_add_u64 v[8:9], v[8:9], 0, v[18:19]
	v_mov_b32_e32 v5, v7
	v_lshl_add_u64 v[8:9], v[4:5], 1, v[8:9]
	s_or_b64 exec, exec, s[4:5]
	global_load_dwordx4 v[120:123], v[8:9], off
	v_mad_i64_i32 v[16:17], s[4:5], v26, s18, 0
	v_add_u32_e32 v5, 0x200, v6
	s_mov_b32 s4, 0x2aaaaaab
	v_mul_hi_i32 v8, v5, s4
	v_lshrrev_b32_e32 v9, 31, v8
	v_ashrrev_i32_e32 v8, 1, v8
	v_add_u32_e32 v8, v8, v9
	v_mul_lo_u32 v9, v8, 12
	v_sub_u32_e32 v10, v5, v9
	v_ashrrev_i32_e32 v9, 31, v8
	v_lshl_add_u64 v[20:21], v[16:17], 0, v[8:9]
	v_cmp_gt_i32_e64 s[4:5], 8, v10
	v_cmp_lt_i32_e32 vcc, 7, v10
	v_lshlrev_b32_e32 v146, 4, v10
	s_and_saveexec_b64 s[6:7], vcc
	s_xor_b64 s[6:7], exec, s[6:7]
	v_lshlrev_b64 v[12:13], 6, v[20:21]
	v_lshl_add_u64 v[12:13], s[72:73], 0, v[12:13]
	v_mov_b32_e32 v147, v195
	s_movk_i32 s18, 0xff80
	v_lshl_add_u64 v[12:13], v[12:13], 0, v[146:147]
	s_mov_b32 s19, -1
	v_lshl_add_u64 v[14:15], v[12:13], 0, s[18:19]
	s_or_saveexec_b64 s[6:7], s[6:7]
	v_lshlrev_b32_e32 v10, 3, v10
	v_ashrrev_i32_e32 v13, 31, v10
	s_xor_b64 exec, exec, s[6:7]
	v_lshlrev_b64 v[14:15], 10, v[20:21]
	v_lshl_add_u64 v[14:15], s[68:69], 0, v[14:15]
	v_mov_b32_e32 v19, v195
	v_lshl_add_u64 v[14:15], v[14:15], 0, v[18:19]
	v_mov_b32_e32 v11, v13
	v_lshl_add_u64 v[14:15], v[10:11], 1, v[14:15]
	s_or_b64 exec, exec, s[6:7]
	global_load_dwordx4 v[124:127], v[14:15], off
	v_add_u32_e32 v11, 0x400, v6
	s_mov_b32 s6, 0x2aaaaaab
	v_mul_hi_i32 v12, v11, s6
	v_lshrrev_b32_e32 v14, 31, v12
	v_ashrrev_i32_e32 v12, 1, v12
	v_add_u32_e32 v14, v12, v14
	v_mul_lo_u32 v12, v14, 12
	v_sub_u32_e32 v11, v11, v12
	v_ashrrev_i32_e32 v15, 31, v14
	v_lshl_add_u64 v[24:25], v[16:17], 0, v[14:15]
	v_cmp_gt_i32_e64 s[6:7], 8, v11
	v_cmp_lt_i32_e32 vcc, 7, v11
	v_lshlrev_b32_e32 v16, 3, v11
	v_lshlrev_b32_e32 v148, 4, v11
	v_lshlrev_b32_e32 v142, 6, v1
	s_and_saveexec_b64 s[18:19], vcc
	s_xor_b64 s[18:19], exec, s[18:19]
	v_lshlrev_b64 v[18:19], 6, v[24:25]
	v_lshl_add_u64 v[18:19], s[72:73], 0, v[18:19]
	v_mov_b32_e32 v149, v195
	s_movk_i32 s20, 0xff80
	v_lshl_add_u64 v[18:19], v[18:19], 0, v[148:149]
	s_mov_b32 s21, -1
	v_mov_b32_e32 v17, v195
	v_lshl_add_u64 v[22:23], v[18:19], 0, s[20:21]
	v_mov_b32_e32 v143, v195
	s_or_saveexec_b64 s[18:19], s[18:19]
	v_mov_b64_e32 v[20:21], v[16:17]
	s_xor_b64 exec, exec, s[18:19]
	v_lshlrev_b64 v[20:21], 10, v[24:25]
	v_lshl_add_u64 v[20:21], s[68:69], 0, v[20:21]
	v_mov_b32_e32 v19, v195
	v_lshl_add_u64 v[18:19], v[20:21], 0, v[18:19]
	v_ashrrev_i32_e32 v17, 31, v16
	v_mov_b32_e32 v143, v195
	v_lshl_add_u64 v[22:23], v[16:17], 1, v[18:19]
	v_mov_b32_e32 v20, v16
	v_mov_b32_e32 v21, v195
	s_or_b64 exec, exec, s[18:19]
	v_ashrrev_i32_e32 v18, 4, v6
	v_ashrrev_i32_e32 v1, 31, v0
	global_load_dwordx4 v[128:131], v[22:23], off
	v_lshlrev_b64 v[22:23], 6, v[0:1]
	v_ashrrev_i32_e32 v19, 31, v18
	v_lshl_add_u64 v[24:25], v[22:23], 0, v[18:19]
	v_mov_b64_e32 v[28:29], s[70:71]
	s_movk_i32 s20, 0x2200
	v_mad_u64_u32 v[30:31], s[18:19], v24, s20, v[28:29]
	v_lshlrev_b32_e32 v1, 4, v6
	v_mad_i32_i24 v31, v25, s20, v31
	v_and_b32_e32 v150, 0xf0, v1
	v_mov_b32_e32 v151, v195
	v_lshl_add_u64 v[24:25], v[30:31], 0, v[150:151]
	v_ashrrev_i32_e32 v30, 4, v5
	v_ashrrev_i32_e32 v31, 31, v30
	v_lshl_add_u64 v[22:23], v[22:23], 0, v[30:31]
	v_mad_u64_u32 v[28:29], s[18:19], v22, s20, v[28:29]
	v_mad_i32_i24 v29, v23, s20, v29
	v_lshl_add_u64 v[22:23], v[28:29], 0, v[150:151]
	global_load_dwordx4 v[132:135], v[24:25], off
	global_load_dwordx4 v[136:139], v[22:23], off
	s_movk_i32 s18, 0xd0
	v_mul_lo_u32 v147, v2, s18
	v_mul_lo_u32 v149, v8, s18
	v_mul_lo_u32 v151, v14, s18
	v_and_b32_e32 v19, 64, v211
	v_lshlrev_b64 v[22:23], 10, v[14:15]
	s_movk_i32 s18, 0x108
	s_mov_b32 s23, 0x440000
	v_xor_b32_e32 v1, 32, v211
	v_mul_lo_u32 v173, v18, s18
	v_mul_lo_u32 v174, v30, s18
	s_waitcnt lgkmcnt(0)
; #define MFMA32(a, b, c) __builtin_amdgcn_mfma_f32_32x32x16_bf16((a), (b), (c), 0, 0, 0)
; DI void attn_tile8(const Params& p, int bh, int qt, char* smem) {
;     ...
;   auto store_tiles = [&](int st) {
;     char* Ks = smem + st * STAGE;
;     char* Vs = Ks + VOFF;
; #pragma unroll
;     for (int i = 0; i < 3; ++i) {
;       const int idx = tid + 512 * i, key = idx / 12, ch = idx % 12;
;       *(u32x4*)(Ks + key * 208 + ch * 16) = rk[i];
;     }
; #pragma unroll
;     for (int i = 0; i < 2; ++i) {
;       const int idx = tid + 512 * i, vd = idx >> 4, ch = idx & 15;
;       uint2* d = (uint2*)(Vs + vd * VROW + ch * 16);
;       d[0] = make_uint2(rv[i].x, rv[i].y);
;       d[1] = make_uint2(rv[i].z, rv[i].w);
;     }
;   };
;   f32x16 O[2];
; #pragma unroll
;   for (int i = 0; i < 16; ++i) { O[0][i] = 0.f; O[1][i] = 0.f; }
;   float m = -1e30f, lsum = 0.f;
;   load_tiles(0);
;   store_tiles(0);
;   __syncthreads();
; #pragma unroll 1
;   for (int kt = 0; kt < nkt; ++kt) {
;     const bool more = kt + 1 < nkt;
;     if (more) load_tiles(kt + 1);
;     ...
;     {
;       bf16x8 kf[2][4];
; #pragma unroll
;       for (int kb = 0; kb < 4; ++kb) kf[0][kb] = *(const bf16x8*)(Ks + (kb * 32 + lr) * 208 + lh * 16);
; #pragma unroll
;       for (int s = 0; s < 6; ++s) {
;         if (s < 5) {
; #pragma unroll
;           for (int kb = 0; kb < 4; ++kb) kf[(s + 1) & 1][kb] = *(const bf16x8*)(Ks + (kb * 32 + lr) * 208 + (s + 1) * 32 + lh * 16);
;         }
;         __builtin_amdgcn_sched_barrier(0);
;         __builtin_amdgcn_s_setprio(1);
; #pragma unroll
;         for (int kb = 0; kb < 4; ++kb) st[kb] = MFMA32(kf[s & 1][kb], qf[s], st[kb]);
;         __builtin_amdgcn_s_setprio(0);
;         __builtin_amdgcn_sched_barrier(0);
;       }
;     }
;     float mx = st[0][0];
; #pragma unroll
;     for (int kb = 0; kb < 4; ++kb)
; #pragma unroll
;       for (int i = 0; i < 16; ++i) mx = fmaxf(mx, st[kb][i]);
;     mx = fmaxf(mx, __shfl_xor(mx, 32));
	v_add_u32_e32 v34, 64, v19
	v_mad_i64_i32 v[18:19], s[18:19], v18, s20, 0
	v_mad_i64_i32 v[30:31], s[18:19], v30, s20, 0
	v_mad_i64_i32 v[22:23], s[18:19], v26, s23, v[22:23]
	v_mul_u32_u24_e32 v171, 0xd0, v27
	v_mul_u32_u24_e32 v172, 0x108, v27
	v_lshlrev_b64 v[14:15], 6, v[14:15]
	v_mov_b64_e32 v[24:25], s[72:73]
	v_lshlrev_b64 v[28:29], 10, v[8:9]
	v_add3_u32 v27, 0, v147, v144
	s_mov_b32 s18, 0x44000
	v_cmp_lt_i32_e32 vcc, v1, v34
	s_mov_b32 s20, 0x88000
	v_add3_u32 v32, 0, v149, v146
	v_lshl_add_u64 v[14:15], v[20:21], 1, v[14:15]
	v_mad_i64_i32 v[152:153], s[18:19], v26, s18, v[24:25]
	v_mad_i64_i32 v[20:21], s[18:19], v26, s23, v[28:29]
	s_waitcnt vmcnt(4)
	ds_write_b128 v27, v[120:123]
	s_waitcnt vmcnt(3)
	ds_write_b128 v32, v[124:127]
	v_cndmask_b32_e32 v27, v211, v1, vcc
	v_mad_i64_i32 v[18:19], s[18:19], v0, s20, v[18:19]
	v_mad_i64_i32 v[0:1], s[18:19], v0, s20, v[30:31]
	v_add_u32_e32 v24, 0, v173
	v_add_u32_e32 v25, 0, v174
	s_mov_b64 s[34:35], 0x1f80
	s_movk_i32 s18, 0x6800
	v_lshl_add_u64 v[154:155], v[14:15], 0, s[34:35]
	v_add3_u32 v14, v24, v150, s18
	v_add3_u32 v15, v25, v150, s18
	v_readlane_b32 s18, v235, 44
	v_or_b32_e32 v0, v0, v150
	v_readlane_b32 s19, v235, 45
	v_mov_b32_e32 v11, v195
	v_mov_b32_e32 v6, v4
	v_lshl_add_u64 v[162:163], s[18:19], 0, v[0:1]
	v_lshlrev_b64 v[0:1], 6, v[8:9]
	v_lshl_add_u64 v[0:1], v[10:11], 1, v[0:1]
	v_or_b32_e32 v18, v18, v150
	v_lshl_add_u64 v[164:165], v[0:1], 0, s[34:35]
	v_lshlrev_b64 v[0:1], 10, v[2:3]
	v_readlane_b32 s20, v235, 46
	v_lshl_add_u64 v[160:161], s[18:19], 0, v[18:19]
	v_mad_i64_i32 v[0:1], s[18:19], v26, s23, v[0:1]
	v_lshl_add_u64 v[6:7], v[142:143], 0, v[6:7]
	v_mov_b32_e32 v12, v10
	v_readlane_b32 s21, v235, 47
	v_lshl_add_u64 v[0:1], v[6:7], 1, v[0:1]
	v_mov_b32_e32 v5, v195
	v_lshl_add_u64 v[16:17], v[16:17], 0, v[142:143]
	v_lshl_add_u64 v[12:13], v[142:143], 0, v[12:13]
	v_lshl_add_u64 v[166:167], s[20:21], 0, v[0:1]
	v_lshlrev_b64 v[0:1], 6, v[2:3]
	v_add3_u32 v33, 0, v151, v148
	v_lshl_add_u64 v[16:17], v[16:17], 1, v[22:23]
	v_lshl_add_u64 v[12:13], v[12:13], 1, v[20:21]
	v_lshl_add_u64 v[0:1], v[4:5], 1, v[0:1]
	v_mov_b32_e32 v176, 0
	v_lshlrev_b32_e32 v145, 3, v170
	s_mov_b32 s31, 0
	v_lshlrev_b32_e32 v175, 2, v27
	v_lshl_add_u64 v[156:157], s[20:21], 0, v[16:17]
	v_lshl_add_u64 v[158:159], s[20:21], 0, v[12:13]
	s_waitcnt vmcnt(2)
	ds_write_b128 v33, v[128:131]
	s_waitcnt vmcnt(1)
	ds_write2_b64 v14, v[132:133], v[134:135] offset1:1
	s_waitcnt vmcnt(0)
	ds_write2_b64 v15, v[136:137], v[138:139] offset1:1
	v_lshl_add_u64 v[168:169], v[0:1], 0, s[34:35]
	v_mov_b32_e32 v178, 0xf149f2ca
	s_mov_b64 s[18:19], 0
	v_mov_b32_e32 v16, 0
	v_mov_b32_e32 v17, v176
	v_mov_b32_e32 v18, v176
	v_mov_b32_e32 v19, v176
	v_mov_b32_e32 v20, v176
	v_mov_b32_e32 v21, v176
	v_mov_b32_e32 v22, v176
	v_mov_b32_e32 v23, v176
	v_mov_b32_e32 v24, v176
	v_mov_b32_e32 v25, v176
	v_mov_b32_e32 v26, v176
	v_mov_b32_e32 v27, v176
	v_mov_b32_e32 v28, v176
	v_mov_b32_e32 v29, v176
	v_mov_b32_e32 v30, v176
	v_mov_b32_e32 v31, v176
	v_mov_b32_e32 v0, 0
	v_mov_b32_e32 v1, v176
	v_mov_b32_e32 v2, v176
	v_mov_b32_e32 v3, v176
	v_mov_b32_e32 v4, v176
	v_mov_b32_e32 v5, v176
	v_mov_b32_e32 v6, v176
	v_mov_b32_e32 v7, v176
	v_mov_b32_e32 v8, v176
	v_mov_b32_e32 v9, v176
	v_mov_b32_e32 v10, v176
	v_mov_b32_e32 v11, v176
	v_mov_b32_e32 v12, v176
	v_mov_b32_e32 v13, v176
	v_mov_b32_e32 v14, v176
	v_mov_b32_e32 v15, v176
	s_waitcnt lgkmcnt(0)
	s_barrier
	v_add_u32_e32 v177, v194, v171
	ds_read_b128 v[180:183], v177 offset:0
	ds_read_b128 v[184:187], v177 offset:32
	ds_read_b128 v[188:191], v177 offset:64
	ds_read_b128 v[200:203], v177 offset:96
	v_sub_u32_e32 v213, 1, v170
	v_mul_u32_u24_e32 v214, 0x3f80, v213
	v_mov_b32_e32 v215, 0
	v_mov_b32_e32 v216, 0
	v_mov_b32_e32 v217, 0
	v_mov_b32_e32 v219, 0
	v_mov_b32_e32 v220, 0
	v_mov_b32_e32 v221, 0
	s_waitcnt lgkmcnt(3)
	v_mfma_f32_32x32x16_bf16 v[80:95], v[180:183], v[96:99], 0
	ds_read_b128 v[180:183], v177 offset:128
	s_waitcnt lgkmcnt(3)
	v_mfma_f32_32x32x16_bf16 v[80:95], v[184:187], v[100:103], v[80:95]
	ds_read_b128 v[184:187], v177 offset:160
	s_waitcnt lgkmcnt(3)
	v_mfma_f32_32x32x16_bf16 v[80:95], v[188:191], v[104:107], v[80:95]
	s_waitcnt lgkmcnt(2)
	v_mfma_f32_32x32x16_bf16 v[80:95], v[200:203], v[108:111], v[80:95]
	s_waitcnt lgkmcnt(1)
	v_mfma_f32_32x32x16_bf16 v[80:95], v[180:183], v[112:115], v[80:95]
	s_waitcnt lgkmcnt(0)
	v_mfma_f32_32x32x16_bf16 v[80:95], v[184:187], v[116:119], v[80:95]
	s_nop 11
	v_max_f32_e32 v232, v80, v81
	v_max3_f32 v232, v232, v82, v83
	v_max3_f32 v232, v232, v84, v85
	v_max3_f32 v232, v232, v86, v87
	v_max3_f32 v232, v232, v88, v89
	v_max3_f32 v232, v232, v90, v91
	v_max3_f32 v232, v232, v92, v93
	v_max3_f32 v232, v232, v94, v95
	ds_bpermute_b32 v233, v175, v232
	s_waitcnt lgkmcnt(0)
	v_max_f32_e32 v213, v232, v233
	v_cvt_pk_bf16_f32 v213, v213, 0
	v_xor_b32_e32 v218, 0x8000, v213
	v_lshlrev_b32_e32 v178, 16, v213
	v_mov_b32_e32 v232, 0
	v_mov_b32_e32 v233, 0
	v_mov_b32_e32 v238, 0
	v_mov_b32_e32 v239, 0
.Lattn_loop:
	s_cmp_lt_u32 s31, 33
	s_cbranch_scc0 .Lattn_noload
	v_lshl_add_u64 v[32:33], v[166:167], 0, s[18:19]
	v_lshl_add_u64 v[34:35], v[152:153], 0, v[168:169]
	v_cndmask_b32_e64 v33, v35, v33, s[2:3]
	v_cndmask_b32_e64 v32, v34, v32, s[2:3]
	global_load_dwordx4 v[120:123], v[32:33], off
	v_lshl_add_u64 v[32:33], v[158:159], 0, s[18:19]
	v_lshl_add_u64 v[34:35], v[152:153], 0, v[164:165]
	v_cndmask_b32_e64 v33, v35, v33, s[4:5]
	v_cndmask_b32_e64 v32, v34, v32, s[4:5]
	global_load_dwordx4 v[124:127], v[32:33], off
	v_lshl_add_u64 v[32:33], v[156:157], 0, s[18:19]
	v_lshl_add_u64 v[34:35], v[152:153], 0, v[154:155]
	v_cndmask_b32_e64 v33, v35, v33, s[6:7]
	v_cndmask_b32_e64 v32, v34, v32, s[6:7]
	global_load_dwordx4 v[128:131], v[32:33], off
	global_load_dwordx4 v[132:135], v[160:161], off
	global_load_dwordx4 v[136:139], v[162:163], off
; #define MFMA32(a, b, c) __builtin_amdgcn_mfma_f32_32x32x16_bf16((a), (b), (c), 0, 0, 0)
; DI void attn_tile8(const Params& p, int bh, int qt, char* smem) {
;     ...
;   for (int kt = 0; kt < nkt; ++kt) {
;     const bool more = kt + 1 < nkt;
;     if (more) load_tiles(kt + 1);
;     const char* Ks = smem + (kt & 1) * STAGE;
;     const char* Vs = Ks + VOFF;
;     f32x16 st[4];
; #pragma unroll
;     for (int kb = 0; kb < 4; ++kb)
; #pragma unroll
;       for (int i = 0; i < 16; ++i) st[kb][i] = 0.f;
;     {
;       bf16x8 kf[2][4];
; #pragma unroll
;       for (int kb = 0; kb < 4; ++kb) kf[0][kb] = *(const bf16x8*)(Ks + (kb * 32 + lr) * 208 + lh * 16);
; #pragma unroll
;       for (int s = 0; s < 6; ++s) {
;         if (s < 5) {
; #pragma unroll
;           for (int kb = 0; kb < 4; ++kb) kf[(s + 1) & 1][kb] = *(const bf16x8*)(Ks + (kb * 32 + lr) * 208 + (s + 1) * 32 + lh * 16);
;         }
;         __builtin_amdgcn_sched_barrier(0);
;         __builtin_amdgcn_s_setprio(1);
; #pragma unroll
;         for (int kb = 0; kb < 4; ++kb) st[kb] = MFMA32(kf[s & 1][kb], qf[s], st[kb]);
;         __builtin_amdgcn_s_setprio(0);
;         __builtin_amdgcn_sched_barrier(0);
;       }
;     }
;     float mx = st[0][0];
; #pragma unroll
;     for (int kb = 0; kb < 4; ++kb)
; #pragma unroll
;       for (int i = 0; i < 16; ++i) mx = fmaxf(mx, st[kb][i]);
;     mx = fmaxf(mx, __shfl_xor(mx, 32));
;     const float mn = fmaxf(m, mx);
;     const float alpha = __builtin_amdgcn_exp2f(m - mn);
;     m = mn;
;     float ps = 0.f;
; #pragma unroll
;     for (int kb = 0; kb < 4; ++kb)
; #pragma unroll
;       for (int i = 0; i < 16; ++i) { st[kb][i] = __builtin_amdgcn_exp2f(st[kb][i] - mn); ps += st[kb][i]; }
;     lsum = lsum * alpha + ps;
; #pragma unroll
;     for (int i = 0; i < 16; ++i) { O[0][i] *= alpha; O[1][i] *= alpha; }
;     {
;       u32x4 vfr[2][2];
; #pragma unroll
;       for (int vb = 0; vb < 2; ++vb) {
;         const char* vp = Vs + (vb * 32 + lr) * VROW + (4 * lh) * 2;
;         const uint2 v0 = *(const uint2*)(vp);
;         const uint2 v1 = *(const uint2*)(vp + 16);
;         vfr[0][vb] = (u32x4){v0.x, v0.y, v1.x, v1.y};
;       }
; #pragma unroll
;       for (int step = 0; step < 8; ++step) {
;         const int kb = step >> 1, s2 = step & 1;
;         if (step < 7) {
;           const int kb2 = (step + 1) >> 1, s22 = (step + 1) & 1;
; #pragma unroll
.Lattn_noload:
	s_add_i32 s23, s31, 1
	s_bitcmp1_b32 s31, 0
	s_cselect_b32 s31, 0xaa00, 0
	v_add3_u32 v177, s31, v194, v171
	v_add3_u32 v213, s31, v145, v172
	v_add_u32_e32 v199, 0x6800, v213
	v_add_u32_e32 v179, 0x8800, v213
	v_max3_f32 v213, v232, v233, 0
	v_cmp_lt_f32_e32 vcc, 0x41000000, v213
	s_cbranch_vccz .Lattn_noresc
	s_nop 1
	v_cndmask_b32_e32 v213, 0, v213, vcc
	v_add_f32_e32 v213, v178, v213
	v_cvt_pk_bf16_f32 v213, v213, 0
	v_xor_b32_e32 v218, 0x8000, v213
	v_lshlrev_b32_e32 v213, 16, v213
	v_sub_f32_e32 v230, v178, v213
	v_mov_b32_e32 v178, v213
	v_exp_f32_e32 v230, v230
	v_add_f32_e32 v238, v238, v239
	v_add_f32_e32 v176, v176, v238
	v_mul_f32_e32 v176, v176, v230
	v_mov_b32_e32 v238, 0
	v_mov_b32_e32 v239, 0
	v_pk_mul_f32 v[16:17], v[16:17], v[230:231] op_sel_hi:[1,0]
	v_pk_mul_f32 v[18:19], v[18:19], v[230:231] op_sel_hi:[1,0]
	v_pk_mul_f32 v[20:21], v[20:21], v[230:231] op_sel_hi:[1,0]
	v_pk_mul_f32 v[22:23], v[22:23], v[230:231] op_sel_hi:[1,0]
	v_pk_mul_f32 v[24:25], v[24:25], v[230:231] op_sel_hi:[1,0]
	v_pk_mul_f32 v[26:27], v[26:27], v[230:231] op_sel_hi:[1,0]
	v_pk_mul_f32 v[28:29], v[28:29], v[230:231] op_sel_hi:[1,0]
	v_pk_mul_f32 v[30:31], v[30:31], v[230:231] op_sel_hi:[1,0]
	v_pk_mul_f32 v[0:1], v[0:1], v[230:231] op_sel_hi:[1,0]
	v_pk_mul_f32 v[2:3], v[2:3], v[230:231] op_sel_hi:[1,0]
	v_pk_mul_f32 v[4:5], v[4:5], v[230:231] op_sel_hi:[1,0]
	v_pk_mul_f32 v[6:7], v[6:7], v[230:231] op_sel_hi:[1,0]
	v_pk_mul_f32 v[8:9], v[8:9], v[230:231] op_sel_hi:[1,0]
	v_pk_mul_f32 v[10:11], v[10:11], v[230:231] op_sel_hi:[1,0]
	v_pk_mul_f32 v[12:13], v[12:13], v[230:231] op_sel_hi:[1,0]
	v_pk_mul_f32 v[14:15], v[14:15], v[230:231] op_sel_hi:[1,0]
.Lattn_noresc:
	ds_read_b128 v[180:183], v177 offset:0
	ds_read_b128 v[184:187], v177 offset:32
	ds_read_b128 v[188:191], v177 offset:64
	ds_read_b128 v[200:203], v177 offset:96
	v_mfma_f32_32x32x16_bf16 v[80:95], v[214:217], v[218:221], 0
	s_waitcnt lgkmcnt(3)
	v_mfma_f32_32x32x16_bf16 v[80:95], v[180:183], v[96:99], v[80:95]
	ds_read_b128 v[180:183], v177 offset:128
	s_waitcnt lgkmcnt(3)
	v_mfma_f32_32x32x16_bf16 v[80:95], v[184:187], v[100:103], v[80:95]
	ds_read_b128 v[184:187], v177 offset:160
	s_waitcnt lgkmcnt(3)
	v_mfma_f32_32x32x16_bf16 v[80:95], v[188:191], v[104:107], v[80:95]
	ds_read_b128 v[188:191], v177 offset:6656
	s_waitcnt lgkmcnt(3)
	v_mfma_f32_32x32x16_bf16 v[80:95], v[200:203], v[108:111], v[80:95]
	ds_read_b128 v[200:203], v177 offset:6688
	s_waitcnt lgkmcnt(3)
	v_mfma_f32_32x32x16_bf16 v[80:95], v[180:183], v[112:115], v[80:95]
	ds_read_b128 v[180:183], v177 offset:6720
	s_waitcnt lgkmcnt(3)
	v_mfma_f32_32x32x16_bf16 v[80:95], v[184:187], v[116:119], v[80:95]
	ds_read_b128 v[184:187], v177 offset:6752
	v_mfma_f32_32x32x16_bf16 v[64:79], v[214:217], v[218:221], 0
	s_waitcnt lgkmcnt(3)
	v_mfma_f32_32x32x16_bf16 v[64:79], v[188:191], v[96:99], v[64:79]
	ds_read_b128 v[188:191], v177 offset:6784
	s_waitcnt lgkmcnt(3)
	v_mfma_f32_32x32x16_bf16 v[64:79], v[200:203], v[100:103], v[64:79]
	ds_read_b128 v[200:203], v177 offset:6816
	s_waitcnt lgkmcnt(3)
	v_mfma_f32_32x32x16_bf16 v[64:79], v[180:183], v[104:107], v[64:79]
	ds_read_b128 v[180:183], v177 offset:13312
	s_nop 0
	v_max_f32_e32 v232, v80, v81
	v_max3_f32 v232, v232, v82, v83
	v_max3_f32 v232, v232, v84, v85
	v_max3_f32 v232, v232, v86, v87
	v_max3_f32 v232, v232, v88, v89
	v_max3_f32 v232, v232, v90, v91
	v_max3_f32 v232, v232, v92, v93
	v_max3_f32 v232, v232, v94, v95
	ds_bpermute_b32 v233, v175, v232
	v_exp_f32_e32 v80, v80
	v_exp_f32_e32 v81, v81
	s_waitcnt lgkmcnt(4)
	v_mfma_f32_32x32x16_bf16 v[64:79], v[184:187], v[108:111], v[64:79]
	ds_read_b128 v[184:187], v177 offset:13344
	v_exp_f32_e32 v82, v82
	v_exp_f32_e32 v83, v83
	v_exp_f32_e32 v84, v84
	v_exp_f32_e32 v85, v85
	v_exp_f32_e32 v86, v86
	v_exp_f32_e32 v87, v87
	v_exp_f32_e32 v88, v88
	v_exp_f32_e32 v89, v89
	v_exp_f32_e32 v90, v90
	v_exp_f32_e32 v91, v91
	s_waitcnt lgkmcnt(4)
	v_mfma_f32_32x32x16_bf16 v[64:79], v[188:191], v[112:115], v[64:79]
	ds_read_b128 v[188:191], v177 offset:13376
	v_exp_f32_e32 v92, v92
	v_exp_f32_e32 v93, v93
	v_exp_f32_e32 v94, v94
	v_exp_f32_e32 v95, v95
	v_pk_add_f32 v[238:239], v[238:239], v[80:81]
	v_pk_add_f32 v[238:239], v[238:239], v[82:83]
	v_pk_add_f32 v[238:239], v[238:239], v[84:85]
	v_pk_add_f32 v[238:239], v[238:239], v[86:87]
	v_pk_add_f32 v[238:239], v[238:239], v[88:89]
	v_pk_add_f32 v[238:239], v[238:239], v[90:91]
	s_waitcnt lgkmcnt(4)
	v_mfma_f32_32x32x16_bf16 v[64:79], v[200:203], v[116:119], v[64:79]
	ds_read_b128 v[200:203], v177 offset:13408
	v_pk_add_f32 v[238:239], v[238:239], v[92:93]
	v_pk_add_f32 v[238:239], v[238:239], v[94:95]
	v_cvt_pk_bf16_f32 v222, v80, v81
	v_cvt_pk_bf16_f32 v223, v82, v83
	v_cvt_pk_bf16_f32 v224, v84, v85
	v_cvt_pk_bf16_f32 v225, v86, v87
	v_cvt_pk_bf16_f32 v226, v88, v89
	v_cvt_pk_bf16_f32 v227, v90, v91
	v_cvt_pk_bf16_f32 v228, v92, v93
	v_cvt_pk_bf16_f32 v229, v94, v95
	ds_read2_b64 v[80:83], v199 offset0:0 offset1:2
	ds_read2_b64 v[84:87], v179 offset0:32 offset1:34
	ds_read2_b64 v[88:91], v199 offset0:4 offset1:6
	ds_read2_b64 v[92:95], v179 offset0:36 offset1:38
	v_mfma_f32_32x32x16_bf16 v[48:63], v[214:217], v[218:221], 0
	s_waitcnt lgkmcnt(8)
	v_mfma_f32_32x32x16_bf16 v[48:63], v[180:183], v[96:99], v[48:63]
	ds_read_b128 v[180:183], v177 offset:13440
	s_waitcnt lgkmcnt(7)
	v_mfma_f32_32x32x16_bf16 v[48:63], v[184:187], v[100:103], v[48:63]
	ds_read_b128 v[184:187], v177 offset:13472
	s_waitcnt lgkmcnt(5)
	v_mfma_f32_32x32x16_bf16 v[16:31], v[80:83], v[222:225], v[16:31]
	v_exp_f32_e32 v64, v64
	v_exp_f32_e32 v65, v65
	v_exp_f32_e32 v66, v66
	v_exp_f32_e32 v67, v67
	s_waitcnt lgkmcnt(4)
; #define MFMA32(a, b, c) __builtin_amdgcn_mfma_f32_32x32x16_bf16((a), (b), (c), 0, 0, 0)
; DI void attn_tile8(const Params& p, int bh, int qt, char* smem) {
;     ...
; #pragma unroll
;     for (int kb = 0; kb < 4; ++kb)
; #pragma unroll
;       for (int i = 0; i < 16; ++i) { st[kb][i] = __builtin_amdgcn_exp2f(st[kb][i] - mn); ps += st[kb][i]; }
;     lsum = lsum * alpha + ps;
; #pragma unroll
;     for (int i = 0; i < 16; ++i) { O[0][i] *= alpha; O[1][i] *= alpha; }
;     {
;       u32x4 vfr[2][2];
; #pragma unroll
;       for (int vb = 0; vb < 2; ++vb) {
;         const char* vp = Vs + (vb * 32 + lr) * VROW + (4 * lh) * 2;
;         const uint2 v0 = *(const uint2*)(vp);
;         const uint2 v1 = *(const uint2*)(vp + 16);
;         vfr[0][vb] = (u32x4){v0.x, v0.y, v1.x, v1.y};
;       }
; #pragma unroll
;       for (int step = 0; step < 8; ++step) {
;         const int kb = step >> 1, s2 = step & 1;
;         if (step < 7) {
;           const int kb2 = (step + 1) >> 1, s22 = (step + 1) & 1;
; #pragma unroll
;           for (int vb = 0; vb < 2; ++vb) {
;             const char* vp = Vs + (vb * 32 + lr) * VROW + (kb2 * 32 + 16 * s22 + 4 * lh) * 2;
;             const uint2 v0 = *(const uint2*)(vp);
;             const uint2 v1 = *(const uint2*)(vp + 16);
;             vfr[(step + 1) & 1][vb] = (u32x4){v0.x, v0.y, v1.x, v1.y};
;           }
;         }
;         u32x4 pk;
;         pk.x = pack2(st[kb][8 * s2 + 0], st[kb][8 * s2 + 1]);
;         pk.y = pack2(st[kb][8 * s2 + 2], st[kb][8 * s2 + 3]);
;         pk.z = pack2(st[kb][8 * s2 + 4], st[kb][8 * s2 + 5]);
;         pk.w = pack2(st[kb][8 * s2 + 6], st[kb][8 * s2 + 7]);
;         const bf16x8 bfrag = __builtin_bit_cast(bf16x8, pk);
;         __builtin_amdgcn_sched_barrier(0);
;         O[0] = MFMA32(__builtin_bit_cast(bf16x8, vfr[step & 1][0]), bfrag, O[0]);
;         O[1] = MFMA32(__builtin_bit_cast(bf16x8, vfr[step & 1][1]), bfrag, O[1]);
;         __builtin_amdgcn_sched_barrier(0);
;       }
;     }
;     if (more) store_tiles((kt + 1) & 1);
;     __syncthreads();
	v_mfma_f32_32x32x16_bf16 v[0:15], v[84:87], v[222:225], v[0:15]
	v_exp_f32_e32 v68, v68
	v_exp_f32_e32 v69, v69
	v_exp_f32_e32 v70, v70
	v_exp_f32_e32 v71, v71
	v_mfma_f32_32x32x16_bf16 v[48:63], v[188:191], v[104:107], v[48:63]
	ds_read_b128 v[188:191], v177 offset:19968
	v_exp_f32_e32 v72, v72
	v_exp_f32_e32 v73, v73
	v_exp_f32_e32 v74, v74
	v_exp_f32_e32 v75, v75
	v_mfma_f32_32x32x16_bf16 v[48:63], v[200:203], v[108:111], v[48:63]
	ds_read_b128 v[200:203], v177 offset:20000
	v_exp_f32_e32 v76, v76
	v_exp_f32_e32 v77, v77
	v_exp_f32_e32 v78, v78
	v_exp_f32_e32 v79, v79
	s_waitcnt lgkmcnt(5)
	v_mfma_f32_32x32x16_bf16 v[16:31], v[88:91], v[226:229], v[16:31]
	v_pk_add_f32 v[238:239], v[238:239], v[64:65]
	v_pk_add_f32 v[238:239], v[238:239], v[66:67]
	v_pk_add_f32 v[238:239], v[238:239], v[68:69]
	v_pk_add_f32 v[238:239], v[238:239], v[70:71]
	s_waitcnt lgkmcnt(4)
	v_mfma_f32_32x32x16_bf16 v[0:15], v[92:95], v[226:229], v[0:15]
	v_pk_add_f32 v[238:239], v[238:239], v[72:73]
	v_pk_add_f32 v[238:239], v[238:239], v[74:75]
	v_pk_add_f32 v[238:239], v[238:239], v[76:77]
	v_pk_add_f32 v[238:239], v[238:239], v[78:79]
	s_waitcnt lgkmcnt(3)
	v_mfma_f32_32x32x16_bf16 v[48:63], v[180:183], v[112:115], v[48:63]
	ds_read_b128 v[180:183], v177 offset:20032
	v_cvt_pk_bf16_f32 v222, v64, v65
	v_cvt_pk_bf16_f32 v223, v66, v67
	v_cvt_pk_bf16_f32 v224, v68, v69
	v_cvt_pk_bf16_f32 v225, v70, v71
	s_waitcnt lgkmcnt(3)
	v_mfma_f32_32x32x16_bf16 v[48:63], v[184:187], v[116:119], v[48:63]
	ds_read_b128 v[184:187], v177 offset:20064
	v_cvt_pk_bf16_f32 v226, v72, v73
	v_cvt_pk_bf16_f32 v227, v74, v75
	v_cvt_pk_bf16_f32 v228, v76, v77
	v_cvt_pk_bf16_f32 v229, v78, v79
	ds_read2_b64 v[64:67], v199 offset0:8 offset1:10
	ds_read2_b64 v[68:71], v179 offset0:40 offset1:42
	ds_read2_b64 v[72:75], v199 offset0:12 offset1:14
	ds_read2_b64 v[76:79], v179 offset0:44 offset1:46
	v_mfma_f32_32x32x16_bf16 v[32:47], v[214:217], v[218:221], 0
	s_waitcnt lgkmcnt(7)
	v_mfma_f32_32x32x16_bf16 v[32:47], v[188:191], v[96:99], v[32:47]
	ds_read_b128 v[188:191], v177 offset:20096
	s_waitcnt lgkmcnt(7)
	v_mfma_f32_32x32x16_bf16 v[32:47], v[200:203], v[100:103], v[32:47]
	ds_read_b128 v[200:203], v177 offset:20128
	s_waitcnt lgkmcnt(5)
	v_mfma_f32_32x32x16_bf16 v[16:31], v[64:67], v[222:225], v[16:31]
	v_exp_f32_e32 v48, v48
	v_exp_f32_e32 v49, v49
	v_exp_f32_e32 v50, v50
	v_exp_f32_e32 v51, v51
	s_waitcnt lgkmcnt(4)
	v_mfma_f32_32x32x16_bf16 v[0:15], v[68:71], v[222:225], v[0:15]
	v_exp_f32_e32 v52, v52
	v_exp_f32_e32 v53, v53
	v_exp_f32_e32 v54, v54
	v_exp_f32_e32 v55, v55
	v_mfma_f32_32x32x16_bf16 v[32:47], v[180:183], v[104:107], v[32:47]
	v_exp_f32_e32 v56, v56
	v_exp_f32_e32 v57, v57
	v_exp_f32_e32 v58, v58
	v_exp_f32_e32 v59, v59
	v_mfma_f32_32x32x16_bf16 v[32:47], v[184:187], v[108:111], v[32:47]
	v_exp_f32_e32 v60, v60
	v_exp_f32_e32 v61, v61
	v_exp_f32_e32 v62, v62
	v_exp_f32_e32 v63, v63
	s_waitcnt lgkmcnt(3)
	v_mfma_f32_32x32x16_bf16 v[16:31], v[72:75], v[226:229], v[16:31]
	v_pk_add_f32 v[238:239], v[238:239], v[48:49]
	v_pk_add_f32 v[238:239], v[238:239], v[50:51]
	v_pk_add_f32 v[238:239], v[238:239], v[52:53]
	v_pk_add_f32 v[238:239], v[238:239], v[54:55]
	s_waitcnt lgkmcnt(2)
	v_mfma_f32_32x32x16_bf16 v[0:15], v[76:79], v[226:229], v[0:15]
	v_pk_add_f32 v[238:239], v[238:239], v[56:57]
	v_pk_add_f32 v[238:239], v[238:239], v[58:59]
	v_pk_add_f32 v[238:239], v[238:239], v[60:61]
	v_pk_add_f32 v[238:239], v[238:239], v[62:63]
	s_waitcnt lgkmcnt(1)
	v_mfma_f32_32x32x16_bf16 v[32:47], v[188:191], v[112:115], v[32:47]
	v_cvt_pk_bf16_f32 v222, v48, v49
	v_cvt_pk_bf16_f32 v223, v50, v51
	v_cvt_pk_bf16_f32 v224, v52, v53
	v_cvt_pk_bf16_f32 v225, v54, v55
	s_waitcnt lgkmcnt(0)
	v_mfma_f32_32x32x16_bf16 v[32:47], v[200:203], v[116:119], v[32:47]
	v_cvt_pk_bf16_f32 v226, v56, v57
	v_cvt_pk_bf16_f32 v227, v58, v59
	v_cvt_pk_bf16_f32 v228, v60, v61
	v_cvt_pk_bf16_f32 v229, v62, v63
	ds_read2_b64 v[48:51], v199 offset0:16 offset1:18
	ds_read2_b64 v[52:55], v179 offset0:48 offset1:50
	ds_read2_b64 v[56:59], v199 offset0:20 offset1:22
	ds_read2_b64 v[60:63], v179 offset0:52 offset1:54
	s_waitcnt lgkmcnt(3)
	v_mfma_f32_32x32x16_bf16 v[16:31], v[48:51], v[222:225], v[16:31]
	s_nop 1
	v_exp_f32_e32 v32, v32
	v_exp_f32_e32 v33, v33
	v_exp_f32_e32 v34, v34
	v_exp_f32_e32 v35, v35
	v_exp_f32_e32 v36, v36
	v_exp_f32_e32 v37, v37
	v_exp_f32_e32 v38, v38
	v_exp_f32_e32 v39, v39
	s_waitcnt lgkmcnt(2)
	v_mfma_f32_32x32x16_bf16 v[0:15], v[52:55], v[222:225], v[0:15]
	v_exp_f32_e32 v40, v40
	v_exp_f32_e32 v41, v41
	v_exp_f32_e32 v42, v42
	v_exp_f32_e32 v43, v43
	v_exp_f32_e32 v44, v44
	v_exp_f32_e32 v45, v45
	v_exp_f32_e32 v46, v46
	v_exp_f32_e32 v47, v47
	s_waitcnt lgkmcnt(1)
	v_mfma_f32_32x32x16_bf16 v[16:31], v[56:59], v[226:229], v[16:31]
	v_pk_add_f32 v[238:239], v[238:239], v[32:33]
	v_pk_add_f32 v[238:239], v[238:239], v[34:35]
	v_pk_add_f32 v[238:239], v[238:239], v[36:37]
	v_pk_add_f32 v[238:239], v[238:239], v[38:39]
	v_pk_add_f32 v[238:239], v[238:239], v[40:41]
	v_pk_add_f32 v[238:239], v[238:239], v[42:43]
	v_pk_add_f32 v[238:239], v[238:239], v[44:45]
	v_pk_add_f32 v[238:239], v[238:239], v[46:47]
	s_waitcnt lgkmcnt(0)
	v_mfma_f32_32x32x16_bf16 v[0:15], v[60:63], v[226:229], v[0:15]
	v_cvt_pk_bf16_f32 v222, v32, v33
	v_cvt_pk_bf16_f32 v223, v34, v35
	v_cvt_pk_bf16_f32 v224, v36, v37
	v_cvt_pk_bf16_f32 v225, v38, v39
	v_cvt_pk_bf16_f32 v226, v40, v41
	v_cvt_pk_bf16_f32 v227, v42, v43
	v_cvt_pk_bf16_f32 v228, v44, v45
	v_cvt_pk_bf16_f32 v229, v46, v47
	ds_read2_b64 v[32:35], v199 offset0:24 offset1:26
	ds_read2_b64 v[36:39], v179 offset0:56 offset1:58
	ds_read2_b64 v[40:43], v199 offset0:28 offset1:30
	ds_read2_b64 v[44:47], v179 offset0:60 offset1:62
	s_bitcmp1_b32 s23, 0
	s_cselect_b32 s20, 0xaa00, 0
	v_add3_u32 v213, s20, v147, v144
	s_waitcnt vmcnt(4)
	ds_write_b128 v213, v[120:123]
	v_add3_u32 v213, s20, v149, v146
	s_waitcnt vmcnt(3)
	ds_write_b128 v213, v[124:127]
	v_add3_u32 v213, s20, v151, v148
	s_waitcnt vmcnt(2)
	ds_write_b128 v213, v[128:131]
	v_add_u32_e32 v213, s20, v173
	s_movk_i32 s21, 0x6800
	v_add3_u32 v213, v213, v150, s21
	s_waitcnt vmcnt(1)
	ds_write2_b64 v213, v[132:133], v[134:135] offset1:1
	v_add_u32_e32 v213, s20, v174
	v_add3_u32 v213, v213, v150, s21
	s_waitcnt vmcnt(0)
	ds_write2_b64 v213, v[136:137], v[138:139] offset1:1
	s_waitcnt lgkmcnt(8)
	v_mfma_f32_32x32x16_bf16 v[16:31], v[32:35], v[222:225], v[16:31]
	s_waitcnt lgkmcnt(7)
	v_mfma_f32_32x32x16_bf16 v[0:15], v[36:39], v[222:225], v[0:15]
	s_waitcnt lgkmcnt(6)
	v_mfma_f32_32x32x16_bf16 v[16:31], v[40:43], v[226:229], v[16:31]
	s_waitcnt lgkmcnt(5)
	v_mfma_f32_32x32x16_bf16 v[0:15], v[44:47], v[226:229], v[0:15]
	s_mov_b64 s[20:21], 0x100
	s_add_u32 s18, s18, 0x20000
	v_lshl_add_u64 v[160:161], v[160:161], 0, s[20:21]
	v_lshl_add_u64 v[162:163], v[162:163], 0, s[20:21]
	s_addc_u32 s19, s19, 0
	s_mov_b64 s[20:21], 0x2000
	s_cmp_lg_u32 s18, 0x440000
	v_lshl_add_u64 v[152:153], v[152:153], 0, s[20:21]
	s_waitcnt lgkmcnt(0)
	s_barrier
; DI void attn_tile8(const Params& p, int bh, int qt, char* smem) {
;     ...
; #pragma unroll 1
;   for (int kt = 0; kt < nkt; ++kt) {
;     const bool more = kt + 1 < nkt;
;     if (more) load_tiles(kt + 1);
;     ...
;   const float ltot = lsum + __shfl_xor(lsum, 32);
;   const float inv = 1.f / ltot;
	s_cbranch_scc0 .Lattn_exit
	s_mov_b32 s31, s23
	s_branch .Lattn_loop
.Lattn_exit:
	v_add_f32_e32 v238, v238, v239
	v_add_f32_e32 v32, v176, v238
	s_branch .LBB1_1139
